# plus krope cache conversion loop unrolled x4 (clamped), like the ckv loop
# speedup vs baseline: 1.0036x; 1.0036x over previous
; DI void phase0(const P& p, char* smem) {
;     ...
;     u16* kr = (u16*)(p.ws + OFF_KROPE);
;     for (int e = gtid; e < 16 * PAST * 4; e += gstride) {
;       const int c8 = e & 3, s = (e >> 2) & 4095, b = e >> 14;
;       const f32x4* src = (const f32x4*)(p.cache_krope + ((size_t)(b * PAST + s) * 32 + c8 * 8));
;       const f32x4 a = __builtin_nontemporal_load(src), c = __builtin_nontemporal_load(src + 1);
;       u32x4 o = {pk2(a.x, a.y), pk2(a.z, a.w), pk2(c.x, c.y), pk2(c.z, c.w)};
;       *(u32x4*)(kr + ((size_t)(NTOK + b * PAST + s) * 32 + c8 * 8)) = o;
;     }
.LBB0_130:
	s_or_b64 exec, exec, s[0:1]
	s_mov_b32 s0, 0x40000
	v_cmp_gt_i32_e32 vcc, s0, v10
	s_and_saveexec_b64 s[0:1], vcc
	s_cbranch_execz .LBB0_133
	s_add_u32 s4, s58, 0x24838100
	s_addc_u32 s5, s59, 0
	s_lshl_b32 s8, s3, 2
	s_lshl_b32 s9, s3, 1
	s_add_i32 s10, s9, s3
	s_mov_b32 s11, 0x40000
	v_mov_b32_e32 v90, v10
	v_mov_b32_e32 v91, 0x3ffff
.Lkr_loop:
	v_min_u32_e32 v92, v90, v91
	v_add_u32_e32 v93, s3, v90
	v_min_u32_e32 v93, v93, v91
	v_add_u32_e32 v94, s9, v90
	v_min_u32_e32 v94, v94, v91
	v_add_u32_e32 v95, s10, v90
	v_min_u32_e32 v95, v95, v91
	v_lshlrev_b32_e32 v96, 5, v92
	v_lshlrev_b32_e32 v97, 5, v93
	v_lshlrev_b32_e32 v98, 5, v94
	v_lshlrev_b32_e32 v99, 5, v95
	global_load_dwordx4 v[100:103], v96, s[22:23] nt
	global_load_dwordx4 v[104:107], v96, s[22:23] offset:16 nt
	global_load_dwordx4 v[108:111], v97, s[22:23] nt
	global_load_dwordx4 v[112:115], v97, s[22:23] offset:16 nt
	global_load_dwordx4 v[116:119], v98, s[22:23] nt
	global_load_dwordx4 v[120:123], v98, s[22:23] offset:16 nt
	global_load_dwordx4 v[124:127], v99, s[22:23] nt
	global_load_dwordx4 v[232:235], v99, s[22:23] offset:16 nt
	v_lshlrev_b32_e32 v92, 4, v92
	v_lshlrev_b32_e32 v93, 4, v93
	v_lshlrev_b32_e32 v94, 4, v94
	v_lshlrev_b32_e32 v95, 4, v95
	v_add_u32_e32 v90, s8, v90
	s_waitcnt vmcnt(6)
	v_cvt_pk_bf16_f32 v100, v100, v101
	v_cvt_pk_bf16_f32 v101, v102, v103
	v_cvt_pk_bf16_f32 v102, v104, v105
	v_cvt_pk_bf16_f32 v103, v106, v107
	global_store_dwordx4 v92, v[100:103], s[4:5]
	s_waitcnt vmcnt(5)
	v_cvt_pk_bf16_f32 v108, v108, v109
	v_cvt_pk_bf16_f32 v109, v110, v111
	v_cvt_pk_bf16_f32 v110, v112, v113
	v_cvt_pk_bf16_f32 v111, v114, v115
	global_store_dwordx4 v93, v[108:111], s[4:5]
	s_waitcnt vmcnt(4)
	v_cvt_pk_bf16_f32 v116, v116, v117
	v_cvt_pk_bf16_f32 v117, v118, v119
	v_cvt_pk_bf16_f32 v118, v120, v121
	v_cvt_pk_bf16_f32 v119, v122, v123
	global_store_dwordx4 v94, v[116:119], s[4:5]
	s_waitcnt vmcnt(3)
	v_cvt_pk_bf16_f32 v124, v124, v125
	v_cvt_pk_bf16_f32 v125, v126, v127
	v_cvt_pk_bf16_f32 v126, v232, v233
	v_cvt_pk_bf16_f32 v127, v234, v235
	global_store_dwordx4 v95, v[124:127], s[4:5]
	v_cmp_gt_u32_e32 vcc, s11, v90
	s_nop 1
	s_and_b64 s[6:7], vcc, exec
	s_cbranch_scc1 .Lkr_loop
